# stack on v129: P9 epilogue stores plain + hot trailing K-tile re-loads (P3/P10) + P10 norm-weight loads hoisted above stats publish + 16KB code warm-up in grid barriers
# speedup vs baseline: 1.0033x; 1.0030x over previous
.LBB0_729:
	s_or_b64 exec, exec, s[0:1]
	s_waitcnt lgkmcnt(0)
	s_barrier
	v_mov_b32_e32 v160, s54
	v_mov_b32_e32 v161, s55
	v_lshl_add_u64 v[162:163], v[130:131], 2, v[160:161]
	global_load_dwordx4 v[176:179], v[162:163], off
	global_load_dwordx4 v[172:175], v[162:163], off offset:64
	global_load_dwordx4 v[168:171], v[162:163], off offset:512
	global_load_dwordx4 v[164:167], v[162:163], off offset:576
	s_add_u32 s0, s58, 0xc0000
	s_addc_u32 s1, s59, 0
	v_cmp_gt_u32_e64 s[2:3], 32, v1
	s_and_saveexec_b64 s[4:5], s[2:3]
	s_cbranch_execz .LBB0_731
	v_lshl_or_b32 v136, s26, 5, v1
	v_lshl_add_u32 v132, v136, 4, 0
	s_waitcnt lgkmcnt(0)
	ds_read_b128 v[132:135], v132
	v_add_u32_e32 v136, s18, v136
	v_ashrrev_i32_e32 v137, 31, v136
	s_ashr_i32 s13, s12, 31
	v_lshl_add_u64 v[136:137], v[136:137], 4, s[0:1]
	s_waitcnt lgkmcnt(0)
	v_mov_b32_e32 v138, v133
	v_mov_b32_e32 v139, v134
	v_mov_b32_e32 v133, v135
	v_pk_add_f32 v[132:133], v[138:139], v[132:133]
	v_lshl_add_u64 v[136:137], s[12:13], 2, v[136:137]
	v_pk_add_f32 v[132:133], v[132:133], v[132:133] op_sel:[0,1] op_sel_hi:[1,0]
	global_store_dword v[136:137], v132, off sc1

.LBB0_734:
	s_or_b64 exec, exec, s[10:11]
	s_waitcnt lgkmcnt(0)
	v_mov_b32_e32 v130, v164
	v_mov_b32_e32 v131, v165
	v_mov_b32_e32 v132, v166
	v_mov_b32_e32 v133, v167
	v_mov_b32_e32 v134, v168
	v_mov_b32_e32 v135, v169
	v_mov_b32_e32 v136, v170
	v_mov_b32_e32 v137, v171
	v_mov_b32_e32 v138, v172
	v_mov_b32_e32 v139, v173
	v_mov_b32_e32 v140, v174
	v_mov_b32_e32 v141, v175
	v_mov_b32_e32 v142, v176
	v_mov_b32_e32 v143, v177
	v_mov_b32_e32 v144, v178
	v_mov_b32_e32 v145, v179
	s_movk_i32 s8, 0x410
	v_or_b32_e32 v146, s16, v152
	v_mul_lo_u32 v147, v150, s8
	v_lshlrev_b32_e32 v146, 2, v146
	v_add_u32_e32 v147, 0, v147
	v_add_u32_e32 v146, v147, v146
	s_cmp_gt_u32 s27, 63
	s_nop 0
	v_pk_mul_f32 v[128:129], v[128:129], v[144:145]
	v_pk_mul_f32 v[126:127], v[126:127], v[142:143]
	s_nop 0
	v_pk_mul_f32 v[124:125], v[124:125], v[140:141]
	v_pk_mul_f32 v[122:123], v[122:123], v[138:139]
	s_nop 0
	v_pk_mul_f32 v[112:113], v[112:113], v[136:137]
	v_pk_mul_f32 v[110:111], v[110:111], v[134:135]
	s_nop 0
	v_pk_mul_f32 v[104:105], v[104:105], v[132:133]
	v_pk_mul_f32 v[102:103], v[102:103], v[130:131]
	v_pk_mul_f32 v[120:121], v[120:121], v[144:145]
	v_pk_mul_f32 v[118:119], v[118:119], v[142:143]
	v_pk_mul_f32 v[116:117], v[116:117], v[140:141]
	v_pk_mul_f32 v[114:115], v[114:115], v[138:139]
	v_pk_mul_f32 v[108:109], v[108:109], v[136:137]
	v_pk_mul_f32 v[106:107], v[106:107], v[134:135]
	v_pk_mul_f32 v[100:101], v[100:101], v[132:133]
	v_pk_mul_f32 v[98:99], v[98:99], v[130:131]
	v_pk_mul_f32 v[96:97], v[96:97], v[144:145]
	v_pk_mul_f32 v[94:95], v[94:95], v[142:143]
	v_pk_mul_f32 v[92:93], v[92:93], v[140:141]
	v_pk_mul_f32 v[90:91], v[90:91], v[138:139]
	v_pk_mul_f32 v[80:81], v[80:81], v[136:137]
	v_pk_mul_f32 v[78:79], v[78:79], v[134:135]
	v_pk_mul_f32 v[72:73], v[72:73], v[132:133]
	v_pk_mul_f32 v[70:71], v[70:71], v[130:131]
	v_pk_mul_f32 v[88:89], v[88:89], v[144:145]
	v_pk_mul_f32 v[86:87], v[86:87], v[142:143]
	v_pk_mul_f32 v[84:85], v[84:85], v[140:141]
	v_pk_mul_f32 v[82:83], v[82:83], v[138:139]
	v_pk_mul_f32 v[76:77], v[76:77], v[136:137]
	v_pk_mul_f32 v[74:75], v[74:75], v[134:135]
	v_pk_mul_f32 v[68:69], v[68:69], v[132:133]
	v_pk_mul_f32 v[66:67], v[66:67], v[130:131]
	ds_write_b128 v146, v[126:129] offset:8192
	ds_write_b128 v146, v[122:125] offset:8256
	ds_write_b128 v146, v[110:113] offset:8704
	ds_write_b128 v146, v[102:105] offset:8768
	ds_write_b128 v146, v[118:121] offset:24832
	ds_write_b128 v146, v[114:117] offset:24896
	ds_write_b128 v146, v[106:109] offset:25344
	ds_write_b128 v146, v[98:101] offset:25408
	ds_write_b128 v146, v[94:97] offset:41472
	ds_write_b128 v146, v[90:93] offset:41536
	ds_write_b128 v146, v[78:81] offset:41984
	ds_write_b128 v146, v[70:73] offset:42048
	ds_write_b128 v146, v[86:89] offset:58112
	ds_write_b128 v146, v[82:85] offset:58176
	ds_write_b128 v146, v[74:77] offset:58624
	ds_write_b128 v146, v[66:69] offset:58688
	s_waitcnt lgkmcnt(0)
	s_barrier
	s_cbranch_scc1 .LBB0_749
	s_memrealtime s[10:11]
	s_lshl_b64 s[6:7], s[6:7], 2
	s_getpc_b64 s[8:9]
	s_add_u32 s8, s8, g_ctl@rel32@lo+65540
	s_addc_u32 s9, s9, g_ctl@rel32@hi+65548
	s_add_u32 s6, s8, s6
	s_addc_u32 s7, s9, s7
	v_mov_b32_e32 v68, 0
	v_mov_b64_e32 v[66:67], 0x1e8481
	s_branch .LBB0_738
